# MLA tile loop: K/V staging LDS addresses precomputed per item (buffer selected by immediate offsets), redundant self-max after bpermute dropped
# baseline (speedup 1.0000x reference)
.LBB0_555:
	s_lshl_b32 s2, s6, 4
	s_add_i32 s2, s7, s2
	s_ashr_i32 s3, s2, 4
	v_mov_b32_e32 v58, v163
	s_mul_i32 s2, s3, 0x1100
	v_readlane_b32 s4, v253, 36
	s_add_i32 s4, s4, s2
	v_and_b32_e32 v125, 15, v58
	v_ashrrev_i32_e32 v0, 1, v58
	v_bfe_u32 v59, v58, 4, 2
	v_and_b32_e32 v0, 0xffffffe0, v0
	s_waitcnt vmcnt(3)
	v_or_b32_e32 v2, s4, v125
	v_readlane_b32 s4, v254, 16
	v_add_u32_e32 v112, v2, v0
	v_lshlrev_b32_e32 v0, 4, v59
	v_readlane_b32 s5, v254, 17
	s_movk_i32 s8, 0xc00
	s_mulk_i32 s3, 0xef00
	v_lshl_add_u64 v[30:31], s[4:5], 0, v[0:1]
	s_waitcnt vmcnt(2)
	v_mad_i64_i32 v[6:7], s[4:5], v112, s8, v[30:31]
	s_waitcnt lgkmcnt(0)
	global_load_dwordx4 v[10:13], v[6:7], off offset:128
	s_addk_i32 s3, 0xff00
	v_add_u32_e32 v2, s3, v112
	v_ashrrev_i32_e32 v32, 6, v2
	v_and_b32_e32 v2, 47, v112
	v_cmp_gt_u32_e32 vcc, 2, v59
	v_readlane_b32 s40, v254, 55
	v_readlane_b32 s50, v255, 1
	v_cndmask_b32_e32 v2, v2, v32, vcc
	v_lshlrev_b32_e32 v2, 4, v2
	v_ashrrev_i32_e32 v3, 31, v2
	v_readlane_b32 s51, v255, 2
	v_cmp_lt_i32_e64 s[4:5], v198, v196
	v_or_b32_e32 v110, 16, v112
	v_lshl_add_u64 v[2:3], v[2:3], 2, s[50:51]
	global_load_dwordx4 v[14:17], v[2:3], off
	global_load_dwordx4 v[18:21], v[2:3], off offset:16
	global_load_dwordx4 v[22:25], v[2:3], off offset:32
	global_load_dwordx4 v[26:29], v[2:3], off offset:48
	v_cndmask_b32_e64 v2, v195, v198, s[4:5]
	v_mad_i64_i32 v[30:31], s[4:5], v110, s8, v[30:31]
	v_lshlrev_b32_e32 v124, 2, v2
	v_bitop3_b32 v33, v112, 63, 16 bitop3:0xc8
	global_load_dwordx4 v[2:5], v[6:7], off
	s_nop 0
	global_load_dwordx4 v[6:9], v[6:7], off offset:64
	v_cndmask_b32_e32 v32, v33, v32, vcc
	global_load_dwordx4 v[42:45], v[30:31], off offset:128
	v_lshlrev_b32_e32 v32, 4, v32
	v_ashrrev_i32_e32 v33, 31, v32
	v_lshl_add_u64 v[32:33], v[32:33], 2, s[50:51]
	global_load_dwordx4 v[38:41], v[32:33], off offset:48
	global_load_dwordx4 v[46:49], v[32:33], off offset:32
	global_load_dwordx4 v[50:53], v[32:33], off offset:16
	global_load_dwordx4 v[54:57], v[32:33], off
	v_and_b32_e32 v68, 16, v58
	v_cmp_eq_u32_e32 vcc, 0, v68
	v_ashrrev_i32_e32 v126, 3, v58
	v_readlane_b32 s4, v254, 18
	v_readlane_b32 s5, v254, 19
	v_readlane_b32 s8, v254, 36
	v_mov_b32_e32 v115, v1
	v_readlane_b32 s9, v254, 37
	v_ashrrev_i32_e32 v128, 2, v58
	v_readlane_b32 s41, v254, 56
	v_readlane_b32 s42, v254, 57
	v_readlane_b32 s43, v254, 58
	v_readlane_b32 s44, v254, 59
	v_readlane_b32 s45, v254, 60
	v_readlane_b32 s46, v254, 61
	v_readlane_b32 s47, v254, 62
	v_readlane_b32 s48, v254, 63
	v_readlane_b32 s49, v255, 0
	v_readlane_b32 s52, v255, 3
	v_readlane_b32 s53, v255, 4
	v_readlane_b32 s54, v255, 5
	v_readlane_b32 s55, v255, 6
	v_readlane_b32 s40, v252, 16
	v_readlane_b32 s42, v252, 18
	v_readlane_b32 s43, v252, 19
	v_mov_b32_e32 v117, v1
	s_waitcnt vmcnt(12)
	v_lshlrev_b32_e32 v131, 2, v59
	v_ashrrev_i32_e32 v113, 31, v112
	v_ashrrev_i32_e32 v111, 31, v110
	v_mov_b32_e32 v140, 0
	v_mov_b32_e32 v138, 0xf149f2ca
	v_mov_b32_e32 v139, 0xf149f2ca
	v_mov_b32_e32 v141, 0
	v_readlane_b32 s41, v252, 17
	v_readlane_b32 s44, v252, 20
	v_readlane_b32 s45, v252, 21
	v_readlane_b32 s46, v252, 22
	v_readlane_b32 s47, v252, 23
	v_readlane_b32 s48, v252, 24
	v_readlane_b32 s49, v252, 25
	v_readlane_b32 s50, v252, 26
	v_readlane_b32 s51, v252, 27
	v_readlane_b32 s52, v252, 28
	v_readlane_b32 s53, v252, 29
	v_readlane_b32 s54, v252, 30
	v_readlane_b32 s55, v252, 31
	s_waitcnt vmcnt(11)
	v_and_b32_e32 v33, 0xffff0000, v10
	v_lshlrev_b32_e32 v32, 16, v10
	v_and_b32_e32 v35, 0xffff0000, v11
	v_lshlrev_b32_e32 v34, 16, v11
	v_and_b32_e32 v11, 0xffff0000, v12
	v_lshlrev_b32_e32 v10, 16, v12
	v_and_b32_e32 v37, 0xffff0000, v13
	v_lshlrev_b32_e32 v36, 16, v13
	ds_bpermute_b32 v12, v124, v32
	ds_bpermute_b32 v13, v124, v33
	ds_bpermute_b32 v60, v124, v34
	ds_bpermute_b32 v61, v124, v35
	ds_bpermute_b32 v62, v124, v10
	ds_bpermute_b32 v63, v124, v11
	s_waitcnt vmcnt(10)
	v_mov_b32_e32 v67, v16
	v_mov_b32_e32 v16, v15
	s_waitcnt vmcnt(9)
	v_mov_b32_e32 v15, v20
	v_mov_b32_e32 v20, v19
	s_waitcnt vmcnt(8)
	v_mov_b32_e32 v19, v24
	v_mov_b32_e32 v24, v23
	s_waitcnt lgkmcnt(4)
	v_pk_mul_f32 v[12:13], v[16:17], v[12:13]
	s_waitcnt lgkmcnt(2)
	v_pk_mul_f32 v[16:17], v[20:21], v[60:61]
	ds_bpermute_b32 v64, v124, v36
	ds_bpermute_b32 v65, v124, v37
	v_mov_b32_e32 v66, v14
	v_mov_b32_e32 v14, v18
	s_waitcnt lgkmcnt(2)
	v_pk_mul_f32 v[20:21], v[24:25], v[62:63]
	v_cndmask_b32_e64 v17, v17, -v17, vcc
	v_cndmask_b32_e64 v16, v16, -v16, vcc
	v_mov_b32_e32 v18, v22
	v_cndmask_b32_e64 v13, v13, -v13, vcc
	v_cndmask_b32_e64 v12, v12, -v12, vcc
	v_cndmask_b32_e64 v21, v21, -v21, vcc
	v_cndmask_b32_e64 v20, v20, -v20, vcc
	v_pk_fma_f32 v[14:15], v[14:15], v[34:35], v[16:17]
	v_pk_fma_f32 v[12:13], v[66:67], v[32:33], v[12:13]
	v_pk_fma_f32 v[10:11], v[18:19], v[10:11], v[20:21]
	v_add_u32_e32 v60, s2, v126
	v_mov_b32_e32 v75, v15
	v_ashrrev_i32_e32 v61, 31, v60
	v_add_u32_e32 v18, 0x200, v58
	s_waitcnt vmcnt(7)
	v_mov_b32_e32 v23, v28
	v_mov_b32_e32 v28, v27
	v_mov_b32_e32 v72, v12
	v_mov_b32_e32 v74, v14
	v_lshlrev_b64 v[14:15], 11, v[60:61]
	v_lshlrev_b32_e32 v12, 4, v58
	v_ashrrev_i32_e32 v127, 3, v18
	s_waitcnt lgkmcnt(0)
	v_pk_mul_f32 v[24:25], v[28:29], v[64:65]
	v_mov_b32_e32 v76, v10
	v_mov_b32_e32 v77, v11
	v_lshl_add_u64 v[10:11], s[4:5], 0, v[14:15]
	v_and_b32_e32 v114, 0x70, v12
	v_add_u32_e32 v62, s2, v127
	v_mov_b32_e32 v22, v26
	v_cndmask_b32_e64 v25, v25, -v25, vcc
	v_cndmask_b32_e64 v24, v24, -v24, vcc
	v_lshl_add_u64 v[10:11], v[10:11], 0, v[114:115]
	v_lshl_add_u64 v[14:15], s[8:9], 0, v[14:15]
	v_ashrrev_i32_e32 v63, 31, v62
	v_pk_fma_f32 v[26:27], v[22:23], v[36:37], v[24:25]
	v_mov_b32_e32 v73, v13
	global_load_dwordx4 v[10:13], v[10:11], off
	v_lshl_add_u64 v[14:15], v[14:15], 0, v[114:115]
	v_lshlrev_b64 v[22:23], 11, v[62:63]
	v_add_u32_e32 v64, s2, v128
	v_lshlrev_b32_e32 v34, 3, v58
	global_load_dwordx4 v[14:17], v[14:15], off
	v_lshl_add_u64 v[18:19], s[4:5], 0, v[22:23]
	v_ashrrev_i32_e32 v65, 31, v64
	v_lshl_add_u64 v[18:19], v[18:19], 0, v[114:115]
	v_lshl_add_u64 v[22:23], s[8:9], 0, v[22:23]
	v_lshlrev_b64 v[28:29], 6, v[64:65]
	v_and_b32_e32 v130, 24, v34
	global_load_dwordx4 v[18:21], v[18:19], off
	v_lshl_add_u64 v[22:23], v[22:23], 0, v[114:115]
	v_lshl_add_u64 v[28:29], s[42:43], 0, v[28:29]
	v_lshlrev_b32_e32 v116, 1, v130
	global_load_dwordx4 v[22:25], v[22:23], off
	v_lshl_add_u64 v[28:29], v[28:29], 0, v[116:117]
	global_load_dwordx4 v[34:37], v[28:29], off
	v_mov_b32_e32 v61, v26
	v_mov_b32_e32 v63, v27
	global_load_dwordx4 v[26:29], v[30:31], off
	s_nop 0
	global_load_dwordx4 v[30:33], v[30:31], off offset:64
	s_waitcnt vmcnt(11)
	v_and_b32_e32 v67, 0xffff0000, v42
	v_lshlrev_b32_e32 v66, 16, v42
	ds_bpermute_b32 v68, v124, v66
	ds_bpermute_b32 v69, v124, v67
	s_waitcnt vmcnt(7)
	v_mov_b32_e32 v71, v56
	v_mov_b32_e32 v56, v55
	v_mov_b32_e32 v70, v54
	v_lshl_add_u64 v[118:119], s[4:5], 0, v[114:115]
	s_waitcnt lgkmcnt(0)
	v_pk_mul_f32 v[54:55], v[56:57], v[68:69]
	v_and_b32_e32 v57, 0xffff0000, v43
	v_lshlrev_b32_e32 v56, 16, v43
	ds_bpermute_b32 v42, v124, v56
	ds_bpermute_b32 v43, v124, v57
	v_cndmask_b32_e64 v55, v55, -v55, vcc
	v_cndmask_b32_e64 v54, v54, -v54, vcc
	v_pk_fma_f32 v[54:55], v[70:71], v[66:67], v[54:55]
	v_mov_b32_e32 v66, v50
	v_mov_b32_e32 v67, v52
	v_mov_b32_e32 v52, v51
	v_and_b32_e32 v51, 0xffff0000, v44
	v_lshlrev_b32_e32 v50, 16, v44
	s_waitcnt lgkmcnt(0)
	v_pk_mul_f32 v[42:43], v[52:53], v[42:43]
	ds_bpermute_b32 v52, v124, v50
	ds_bpermute_b32 v53, v124, v51
	v_cndmask_b32_e64 v43, v43, -v43, vcc
	v_cndmask_b32_e64 v42, v42, -v42, vcc
	v_pk_fma_f32 v[42:43], v[66:67], v[56:57], v[42:43]
	v_mov_b32_e32 v57, v48
	v_mov_b32_e32 v48, v47
	v_mov_b32_e32 v56, v46
	s_waitcnt lgkmcnt(0)
	v_pk_mul_f32 v[46:47], v[48:49], v[52:53]
	v_and_b32_e32 v49, 0xffff0000, v45
	v_lshlrev_b32_e32 v48, 16, v45
	ds_bpermute_b32 v44, v124, v48
	ds_bpermute_b32 v45, v124, v49
	v_cndmask_b32_e64 v47, v47, -v47, vcc
	v_cndmask_b32_e64 v46, v46, -v46, vcc
	v_pk_fma_f32 v[46:47], v[56:57], v[50:51], v[46:47]
	v_mov_b32_e32 v51, v40
	v_mov_b32_e32 v40, v39
	v_mov_b32_e32 v50, v38
	s_waitcnt lgkmcnt(0)
	v_pk_mul_f32 v[38:39], v[40:41], v[44:45]
	v_cndmask_b32_e64 v39, v39, -v39, vcc
	v_cndmask_b32_e64 v38, v38, -v38, vcc
	v_pk_fma_f32 v[38:39], v[50:51], v[48:49], v[38:39]
	v_mov_b32_e32 v44, v47
	v_mov_b32_e32 v45, v38
	v_mov_b32_e32 v47, v39
	v_mad_u64_u32 v[38:39], s[2:3], v126, s12, v[114:115]
	v_lshlrev_b32_e32 v39, 6, v126
	s_waitcnt vmcnt(6)
	ds_write_b128 v38, v[10:13]
	v_sub_u32_e32 v38, v38, v39
	v_cmp_lt_i32_e32 vcc, v197, v196
	s_waitcnt vmcnt(5)
	ds_write_b128 v38, v[14:17] offset:53248
	v_mad_u64_u32 v[38:39], s[2:3], v127, s12, v[114:115]
	v_lshlrev_b32_e32 v39, 6, v127
	s_waitcnt vmcnt(4)
	ds_write_b128 v38, v[18:21]
	v_sub_u32_e32 v38, v38, v39
	s_waitcnt vmcnt(3)
	ds_write_b128 v38, v[22:25] offset:53248
	v_mad_u64_u32 v[38:39], s[2:3], v128, s12, v[116:117]
	s_waitcnt vmcnt(2)
	ds_write_b128 v38, v[34:37] offset:128
	v_cndmask_b32_e32 v38, v195, v197, vcc
	v_lshlrev_b32_e32 v129, 2, v38
	v_bfe_u32 v38, v58, 2, 2
	v_mov_b32_e32 v48, v1
	v_mov_b32_e32 v49, v1
	v_or_b32_e32 v132, v131, v38
	v_cvt_pk_bf16_f32 v41, v61, v63
	v_cvt_pk_bf16_f32 v40, v76, v77
	v_cvt_pk_bf16_f32 v39, v74, v75
	v_cvt_pk_bf16_f32 v38, v72, v73
	v_cvt_pk_bf16_f32 v45, v45, v47
	v_cvt_pk_bf16_f32 v44, v46, v44
	v_cvt_pk_bf16_f32 v43, v42, v43
	v_cvt_pk_bf16_f32 v42, v54, v55
	v_lshl_add_u64 v[120:121], s[8:9], 0, v[114:115]
	v_lshl_add_u64 v[122:123], s[42:43], 0, v[116:117]
	v_add_u32_e32 v115, 0x80, v64
	v_add_u32_e32 v117, 0x80, v62
	v_add_u32_e32 v137, 0x80, v60
	v_mov_b32_e32 v46, v1
	v_mov_b32_e32 v47, v1
	v_mov_b64_e32 v[64:65], v[48:49]
	v_mov_b64_e32 v[52:53], v[48:49]
	v_mov_b64_e32 v[68:69], v[48:49]
	v_mov_b64_e32 v[56:57], v[48:49]
	v_mov_b64_e32 v[72:73], v[48:49]
	v_mov_b64_e32 v[60:61], v[48:49]
	v_mov_b64_e32 v[76:77], v[48:49]
	v_or_b32_e32 v133, 0xd000, v130
	v_or_b32_e32 v134, 0xd020, v130
	v_or_b32_e32 v135, 0xd040, v130
	v_or_b32_e32 v136, 0xd060, v130
	s_mov_b32 s4, 0
	v_mov_b64_e32 v[62:63], v[46:47]
	v_mov_b64_e32 v[50:51], v[46:47]
	v_mov_b64_e32 v[66:67], v[46:47]
	v_mov_b64_e32 v[54:55], v[46:47]
	v_mov_b64_e32 v[70:71], v[46:47]
	v_mov_b64_e32 v[58:59], v[46:47]
	v_mov_b64_e32 v[74:75], v[46:47]
	v_mad_u32_u24 v224, v126, s12, v114
	v_mad_u32_u24 v225, v126, s16, v114
	v_mad_u32_u24 v226, v127, s12, v114
	v_mad_u32_u24 v227, v127, s16, v114
	v_mad_u32_u24 v228, v128, s12, v116
	v_add_u32_e32 v229, 0x4800, v225
	v_add_u32_e32 v230, 0x4800, v227
	s_waitcnt vmcnt(0)
	s_waitcnt lgkmcnt(0)
	s_barrier
	s_branch .LBB0_557

.LBB0_559:
	s_and_b32 s5, s4, 0x80
	v_or_b32_e32 v142, s5, v125
	v_mad_u32_u24 v143, v142, s12, v0
	ds_read_b128 v[78:81], v143
	ds_read_b128 v[82:85], v143 offset:64
	ds_read_b128 v[86:89], v143 offset:128
	ds_read_b128 v[94:97], v143 offset:3328
	ds_read_b128 v[98:101], v143 offset:3392
	ds_read_b128 v[144:147], v143 offset:3456
	s_setprio 1
	s_waitcnt lgkmcnt(5)
	v_mfma_f32_16x16x32_bf16 v[90:93], v[78:81], v[2:5], 0
	v_mfma_f32_16x16x32_bf16 v[78:81], v[78:81], v[26:29], 0
	s_waitcnt lgkmcnt(4)
	v_mfma_f32_16x16x32_bf16 v[90:93], v[82:85], v[6:9], v[90:93]
	v_mfma_f32_16x16x32_bf16 v[78:81], v[82:85], v[30:33], v[78:81]
	s_waitcnt lgkmcnt(3)
	v_mfma_f32_16x16x32_bf16 v[106:109], v[86:89], v[38:41], v[90:93]
	v_mfma_f32_16x16x32_bf16 v[90:93], v[86:89], v[42:45], v[78:81]
	s_waitcnt lgkmcnt(2)
	v_mfma_f32_16x16x32_bf16 v[78:81], v[94:97], v[2:5], 0
	v_mfma_f32_16x16x32_bf16 v[82:85], v[94:97], v[26:29], 0
	s_waitcnt lgkmcnt(1)
	v_mfma_f32_16x16x32_bf16 v[78:81], v[98:101], v[6:9], v[78:81]
	v_mfma_f32_16x16x32_bf16 v[82:85], v[98:101], v[30:33], v[82:85]
	s_waitcnt lgkmcnt(0)
	v_mfma_f32_16x16x32_bf16 v[102:105], v[144:147], v[38:41], v[78:81]
	v_mfma_f32_16x16x32_bf16 v[82:85], v[144:147], v[42:45], v[82:85]
	s_setprio 0
	s_nop 2
	ds_read_b128 v[78:81], v143 offset:6656
	ds_read_b128 v[86:89], v143 offset:6720
	ds_read_b128 v[94:97], v143 offset:6784
	ds_read_b128 v[144:147], v143 offset:9984
	ds_read_b128 v[148:151], v143 offset:10048
	ds_read_b128 v[152:155], v143 offset:10112
	s_setprio 1
	s_waitcnt lgkmcnt(5)
	v_mfma_f32_16x16x32_bf16 v[98:101], v[78:81], v[2:5], 0
	v_mfma_f32_16x16x32_bf16 v[78:81], v[78:81], v[26:29], 0
	s_waitcnt lgkmcnt(4)
	v_mfma_f32_16x16x32_bf16 v[98:101], v[86:89], v[6:9], v[98:101]
	v_mfma_f32_16x16x32_bf16 v[78:81], v[86:89], v[30:33], v[78:81]
	s_waitcnt lgkmcnt(3)
	v_mfma_f32_16x16x32_bf16 v[98:101], v[94:97], v[38:41], v[98:101]
	v_mfma_f32_16x16x32_bf16 v[86:89], v[94:97], v[42:45], v[78:81]
	s_waitcnt lgkmcnt(2)
	v_mfma_f32_16x16x32_bf16 v[78:81], v[144:147], v[2:5], 0
	v_mfma_f32_16x16x32_bf16 v[94:97], v[144:147], v[26:29], 0
	s_waitcnt lgkmcnt(1)
	v_mfma_f32_16x16x32_bf16 v[78:81], v[148:151], v[6:9], v[78:81]
	v_mfma_f32_16x16x32_bf16 v[144:147], v[148:151], v[30:33], v[94:97]
	s_waitcnt lgkmcnt(0)
	v_mfma_f32_16x16x32_bf16 v[94:97], v[152:155], v[38:41], v[78:81]
	v_mfma_f32_16x16x32_bf16 v[78:81], v[152:155], v[42:45], v[144:147]
	s_setprio 0
	v_max3_f32 v143, v106, s18, v107
	v_max3_f32 v143, v143, v108, v109
	v_max3_f32 v143, v143, v102, v103
	v_max3_f32 v143, v143, v104, v105
	v_max3_f32 v143, v143, v98, v99
	v_max3_f32 v143, v143, v100, v101
	v_max3_f32 v143, v143, v94, v95
	v_max3_f32 v143, v143, v96, v97
	v_mul_f32_e32 v143, 0x3e16c740, v143
	ds_bpermute_b32 v144, v124, v143
	s_waitcnt lgkmcnt(0)
	v_max_f32_e32 v143, v143, v144
	ds_bpermute_b32 v144, v129, v143
	s_waitcnt lgkmcnt(0)
	v_max_f32_e32 v143, v143, v144
	v_add_f32_e32 v144, 0x41000000, v139
	v_cmp_gt_f32_e32 vcc, v143, v144
	s_cbranch_vccz .LBB0_561
	v_max_f32_e32 v143, v143, v143
	v_max_f32_e32 v144, v139, v139
	v_max_f32_e32 v143, v144, v143
	v_sub_f32_e32 v139, v139, v143
	v_exp_f32_e32 v144, v139
	v_mov_b32_e32 v139, v143
	v_mul_f32_e32 v141, v141, v144
	v_pk_mul_f32 v[76:77], v[76:77], v[144:145] op_sel_hi:[1,0]
	v_pk_mul_f32 v[74:75], v[74:75], v[144:145] op_sel_hi:[1,0]
	v_pk_mul_f32 v[72:73], v[72:73], v[144:145] op_sel_hi:[1,0]
	v_pk_mul_f32 v[70:71], v[70:71], v[144:145] op_sel_hi:[1,0]
	v_pk_mul_f32 v[68:69], v[68:69], v[144:145] op_sel_hi:[1,0]
	v_pk_mul_f32 v[66:67], v[66:67], v[144:145] op_sel_hi:[1,0]
	v_pk_mul_f32 v[64:65], v[64:65], v[144:145] op_sel_hi:[1,0]
	v_pk_mul_f32 v[62:63], v[62:63], v[144:145] op_sel_hi:[1,0]
.LBB0_561:
	v_max3_f32 v143, v90, s18, v91
	v_max3_f32 v143, v143, v92, v93
	v_max3_f32 v143, v143, v82, v83
	v_max3_f32 v143, v143, v84, v85
	v_max3_f32 v143, v143, v86, v87
	v_max3_f32 v143, v143, v88, v89
	v_max3_f32 v143, v143, v78, v79
	v_max3_f32 v143, v143, v80, v81
	v_mul_f32_e32 v143, 0x3e16c740, v143
	ds_bpermute_b32 v144, v124, v143
	s_waitcnt lgkmcnt(0)
	v_max_f32_e32 v143, v143, v144
	ds_bpermute_b32 v144, v129, v143
	s_waitcnt lgkmcnt(0)
	v_max_f32_e32 v143, v143, v144
	v_add_f32_e32 v144, 0x41000000, v138
	v_cmp_gt_f32_e32 vcc, v143, v144
	s_cbranch_vccz .LBB0_563
	v_max_f32_e32 v143, v143, v143
	v_max_f32_e32 v144, v138, v138
	v_max_f32_e32 v143, v144, v143
	v_sub_f32_e32 v138, v138, v143
	v_exp_f32_e32 v138, v138
	s_nop 0
	v_mul_f32_e32 v140, v140, v138
	v_pk_mul_f32 v[60:61], v[60:61], v[138:139] op_sel_hi:[1,0]
	v_pk_mul_f32 v[58:59], v[58:59], v[138:139] op_sel_hi:[1,0]
	v_pk_mul_f32 v[56:57], v[56:57], v[138:139] op_sel_hi:[1,0]
	v_pk_mul_f32 v[54:55], v[54:55], v[138:139] op_sel_hi:[1,0]
	v_pk_mul_f32 v[52:53], v[52:53], v[138:139] op_sel_hi:[1,0]
	v_pk_mul_f32 v[50:51], v[50:51], v[138:139] op_sel_hi:[1,0]
	v_pk_mul_f32 v[48:49], v[48:49], v[138:139] op_sel_hi:[1,0]
	v_pk_mul_f32 v[46:47], v[46:47], v[138:139] op_sel_hi:[1,0]
	v_mov_b32_e32 v138, v143
.LBB0_563:
	v_fma_f32 v106, v106, s21, -v139
	v_exp_f32_e32 v106, v106
	v_fma_f32 v107, v107, s21, -v139
	v_exp_f32_e32 v107, v107
	v_fma_f32 v108, v108, s21, -v139
	v_exp_f32_e32 v108, v108
	v_fma_f32 v109, v109, s21, -v139
	v_exp_f32_e32 v109, v109
	v_fma_f32 v102, v102, s21, -v139
	v_mul_u32_u24_e32 v160, 0xd0, v142
	v_add_f32_e32 v142, 0, v106
	v_exp_f32_e32 v102, v102
	v_fma_f32 v103, v103, s21, -v139
	v_add_f32_e32 v142, v107, v142
	v_exp_f32_e32 v103, v103
	v_fma_f32 v104, v104, s21, -v139
	v_add_f32_e32 v142, v108, v142
	v_exp_f32_e32 v104, v104
	v_fma_f32 v105, v105, s21, -v139
	v_add_f32_e32 v142, v109, v142
	v_exp_f32_e32 v105, v105
	v_fma_f32 v98, v98, s21, -v139
	v_cvt_pk_bf16_f32 v106, v106, v107
	v_cvt_pk_bf16_f32 v107, v108, v109
	v_add_f32_e32 v108, v102, v142
	v_exp_f32_e32 v98, v98
	v_fma_f32 v99, v99, s21, -v139
	v_add_f32_e32 v108, v103, v108
	v_exp_f32_e32 v99, v99
	v_fma_f32 v100, v100, s21, -v139
	v_add_f32_e32 v108, v104, v108
	v_exp_f32_e32 v100, v100
	v_fma_f32 v101, v101, s21, -v139
	v_add_f32_e32 v142, v105, v108
	v_exp_f32_e32 v101, v101
	v_fma_f32 v94, v94, s21, -v139
	v_cvt_pk_bf16_f32 v108, v102, v103
	v_add_f32_e32 v102, v98, v142
	v_exp_f32_e32 v94, v94
	v_fma_f32 v95, v95, s21, -v139
	v_add_f32_e32 v102, v99, v102
	v_exp_f32_e32 v95, v95
	v_fma_f32 v96, v96, s21, -v139
	v_add_f32_e32 v102, v100, v102
	v_exp_f32_e32 v96, v96
	v_fma_f32 v97, v97, s21, -v139
	v_add_f32_e32 v102, v101, v102
	v_exp_f32_e32 v97, v97
	v_cvt_pk_bf16_f32 v98, v98, v99
	v_cvt_pk_bf16_f32 v99, v100, v101
	v_add_f32_e32 v100, v94, v102
	v_add_f32_e32 v100, v95, v100
	v_add_f32_e32 v100, v96, v100
	v_fma_f32 v90, v90, s21, -v138
	v_fma_f32 v86, v86, s21, -v138
	v_fma_f32 v78, v78, s21, -v138
	v_add_f32_e32 v102, v97, v100
	v_cvt_pk_bf16_f32 v100, v94, v95
	v_or_b32_e32 v94, s5, v132
	v_exp_f32_e32 v144, v90
	v_fma_f32 v90, v91, s21, -v138
	v_exp_f32_e32 v159, v86
	v_fma_f32 v86, v87, s21, -v138
	v_exp_f32_e32 v154, v78
	v_fma_f32 v78, v79, s21, -v138
	v_exp_f32_e32 v145, v90
	v_fma_f32 v90, v92, s21, -v138
	v_exp_f32_e32 v146, v86
	v_fma_f32 v86, v88, s21, -v138
	v_exp_f32_e32 v151, v78
	v_fma_f32 v78, v80, s21, -v138
	v_mul_u32_u24_e32 v143, 0x48, v94
	v_exp_f32_e32 v147, v90
	v_fma_f32 v90, v93, s21, -v138
	v_exp_f32_e32 v148, v86
	v_fma_f32 v86, v89, s21, -v138
	v_exp_f32_e32 v152, v78
	v_fma_f32 v78, v81, s21, -v138
	v_lshl_add_u32 v142, v143, 1, v130
	v_cvt_pk_bf16_f32 v101, v96, v97
	v_exp_f32_e32 v149, v90
	v_exp_f32_e32 v150, v86
	v_exp_f32_e32 v155, v78
	ds_read_b64_tr_b16 v[80:81], v142 offset:55552
	ds_read_b64_tr_b16 v[78:79], v142 offset:53248
	ds_read_b64_tr_b16 v[88:89], v142 offset:55584
	ds_read_b64_tr_b16 v[86:87], v142 offset:53280
	ds_read_b64_tr_b16 v[90:91], v142 offset:57856
	ds_read_b64_tr_b16 v[92:93], v142 offset:60160
	ds_read_b64_tr_b16 v[96:97], v142 offset:60192
	ds_read_b64_tr_b16 v[94:95], v142 offset:57888
	v_fma_f32 v82, v82, s21, -v138
	v_exp_f32_e32 v153, v82
	v_fma_f32 v82, v83, s21, -v138
	v_exp_f32_e32 v156, v82
	v_fma_f32 v82, v84, s21, -v138
	v_exp_f32_e32 v157, v82
	v_fma_f32 v82, v85, s21, -v138
	v_exp_f32_e32 v158, v82
	v_cvt_pk_bf16_f32 v109, v104, v105
	v_add_f32_e32 v141, v141, v102
	v_cvt_pk_bf16_f32 v82, v144, v145
	v_cvt_pk_bf16_f32 v83, v147, v149
	v_cvt_pk_bf16_f32 v84, v153, v156
	v_cvt_pk_bf16_f32 v85, v157, v158
	v_cvt_pk_bf16_f32 v102, v159, v146
	v_cvt_pk_bf16_f32 v103, v148, v150
	v_cvt_pk_bf16_f32 v104, v154, v151
	v_cvt_pk_bf16_f32 v105, v152, v155
	s_setprio 1
	s_waitcnt lgkmcnt(6)
	v_mfma_f32_16x16x32_bf16 v[74:77], v[78:81], v[106:109], v[74:77]
	v_mfma_f32_16x16x32_bf16 v[58:61], v[78:81], v[82:85], v[58:61]
	s_waitcnt lgkmcnt(4)
	v_mfma_f32_16x16x32_bf16 v[70:73], v[86:89], v[106:109], v[70:73]
	v_mfma_f32_16x16x32_bf16 v[78:81], v[86:89], v[82:85], v[54:57]
	s_waitcnt lgkmcnt(2)
	v_mfma_f32_16x16x32_bf16 v[74:77], v[90:93], v[98:101], v[74:77]
	v_mfma_f32_16x16x32_bf16 v[58:61], v[90:93], v[102:105], v[58:61]
	s_waitcnt lgkmcnt(0)
	v_mfma_f32_16x16x32_bf16 v[54:57], v[94:97], v[98:101], v[70:73]
	v_mfma_f32_16x16x32_bf16 v[70:73], v[94:97], v[102:105], v[78:81]
	s_setprio 0
	s_nop 1
	ds_read_b64_tr_b16 v[80:81], v142 offset:55616
	ds_read_b64_tr_b16 v[78:79], v142 offset:53312
	ds_read_b64_tr_b16 v[88:89], v142 offset:55648
	ds_read_b64_tr_b16 v[86:87], v142 offset:53344
	ds_read_b64_tr_b16 v[90:91], v142 offset:57920
	ds_read_b64_tr_b16 v[92:93], v142 offset:60224
	ds_read_b64_tr_b16 v[96:97], v142 offset:60256
	ds_read_b64_tr_b16 v[94:95], v142 offset:57952
	s_setprio 1
	s_waitcnt lgkmcnt(6)
	v_mfma_f32_16x16x32_bf16 v[66:69], v[78:81], v[106:109], v[66:69]
	v_mfma_f32_16x16x32_bf16 v[78:81], v[78:81], v[82:85], v[50:53]
	s_waitcnt lgkmcnt(2)
	v_mfma_f32_16x16x32_bf16 v[50:53], v[90:93], v[98:101], v[66:69]
	v_mfma_f32_16x16x32_bf16 v[66:69], v[90:93], v[102:105], v[78:81]
	v_mfma_f32_16x16x32_bf16 v[62:65], v[86:89], v[106:109], v[62:65]
	v_mfma_f32_16x16x32_bf16 v[78:81], v[86:89], v[82:85], v[46:49]
	s_waitcnt lgkmcnt(0)
	v_mfma_f32_16x16x32_bf16 v[46:49], v[94:97], v[98:101], v[62:65]
	v_mfma_f32_16x16x32_bf16 v[62:65], v[94:97], v[102:105], v[78:81]
	s_setprio 0
	v_add_u32_e32 v160, v0, v160
	s_nop 2
	ds_read_b128 v[78:81], v160 offset:13312
	ds_read_b128 v[82:85], v160 offset:13376
	ds_read_b128 v[86:89], v160 offset:13440
	ds_read_b128 v[94:97], v160 offset:16640
	ds_read_b128 v[98:101], v160 offset:16704
	ds_read_b128 v[102:105], v160 offset:16768
	s_setprio 1
	s_waitcnt lgkmcnt(5)
	v_mfma_f32_16x16x32_bf16 v[90:93], v[78:81], v[2:5], 0
	v_mfma_f32_16x16x32_bf16 v[78:81], v[78:81], v[26:29], 0
	s_waitcnt lgkmcnt(4)
	v_mfma_f32_16x16x32_bf16 v[90:93], v[82:85], v[6:9], v[90:93]
	v_mfma_f32_16x16x32_bf16 v[78:81], v[82:85], v[30:33], v[78:81]
	s_waitcnt lgkmcnt(3)
	v_mfma_f32_16x16x32_bf16 v[106:109], v[86:89], v[38:41], v[90:93]
	v_mfma_f32_16x16x32_bf16 v[90:93], v[86:89], v[42:45], v[78:81]
	s_waitcnt lgkmcnt(2)
	v_mfma_f32_16x16x32_bf16 v[78:81], v[94:97], v[2:5], 0
	v_mfma_f32_16x16x32_bf16 v[82:85], v[94:97], v[26:29], 0
	s_waitcnt lgkmcnt(1)
	v_mfma_f32_16x16x32_bf16 v[78:81], v[98:101], v[6:9], v[78:81]
	v_mfma_f32_16x16x32_bf16 v[82:85], v[98:101], v[30:33], v[82:85]
	s_waitcnt lgkmcnt(0)
	v_mfma_f32_16x16x32_bf16 v[98:101], v[102:105], v[38:41], v[78:81]
	v_mfma_f32_16x16x32_bf16 v[82:85], v[102:105], v[42:45], v[82:85]
	s_setprio 0
	s_nop 2
	ds_read_b128 v[78:81], v160 offset:19968
	ds_read_b128 v[86:89], v160 offset:20032
	ds_read_b128 v[94:97], v160 offset:20096
	ds_read_b128 v[164:167], v160 offset:23296
	ds_read_b128 v[168:171], v160 offset:23360
	ds_read_b128 v[172:175], v160 offset:23424
	s_setprio 1
	s_waitcnt lgkmcnt(5)
	v_mfma_f32_16x16x32_bf16 v[102:105], v[78:81], v[2:5], 0
	v_mfma_f32_16x16x32_bf16 v[78:81], v[78:81], v[26:29], 0
	s_waitcnt lgkmcnt(4)
	v_mfma_f32_16x16x32_bf16 v[102:105], v[86:89], v[6:9], v[102:105]
	v_mfma_f32_16x16x32_bf16 v[78:81], v[86:89], v[30:33], v[78:81]
	s_waitcnt lgkmcnt(3)
	v_mfma_f32_16x16x32_bf16 v[102:105], v[94:97], v[38:41], v[102:105]
	v_mfma_f32_16x16x32_bf16 v[86:89], v[94:97], v[42:45], v[78:81]
	s_waitcnt lgkmcnt(2)
	v_mfma_f32_16x16x32_bf16 v[78:81], v[164:167], v[2:5], 0
	v_mfma_f32_16x16x32_bf16 v[94:97], v[164:167], v[26:29], 0
	s_waitcnt lgkmcnt(1)
	v_mfma_f32_16x16x32_bf16 v[78:81], v[168:171], v[6:9], v[78:81]
	v_mfma_f32_16x16x32_bf16 v[164:167], v[168:171], v[30:33], v[94:97]
	s_waitcnt lgkmcnt(0)
	v_mfma_f32_16x16x32_bf16 v[94:97], v[172:175], v[38:41], v[78:81]
	v_mfma_f32_16x16x32_bf16 v[78:81], v[172:175], v[42:45], v[164:167]
	s_setprio 0
	v_max3_f32 v160, v106, s18, v107
	v_max3_f32 v160, v160, v108, v109
	v_max3_f32 v160, v160, v98, v99
	v_max3_f32 v160, v160, v100, v101
	v_max3_f32 v160, v160, v102, v103
	v_max3_f32 v160, v160, v104, v105
	v_max3_f32 v160, v160, v94, v95
	v_max3_f32 v160, v160, v96, v97
	v_mul_f32_e32 v160, 0x3e16c740, v160
	ds_bpermute_b32 v161, v124, v160
	s_waitcnt lgkmcnt(0)
	v_max_f32_e32 v160, v160, v161
	ds_bpermute_b32 v161, v129, v160
	s_waitcnt lgkmcnt(0)
	v_max_f32_e32 v160, v160, v161
	v_add_f32_e32 v161, 0x41000000, v139
	v_cmp_gt_f32_e32 vcc, v160, v161
	s_cbranch_vccz .LBB0_565
	v_max_f32_e32 v160, v160, v160
	v_max_f32_e32 v161, v139, v139
	v_max_f32_e32 v161, v161, v160
	v_sub_f32_e32 v139, v139, v161
	v_exp_f32_e32 v160, v139
	v_mov_b32_e32 v139, v161
	v_mul_f32_e32 v141, v141, v160
	v_pk_mul_f32 v[76:77], v[76:77], v[160:161] op_sel_hi:[1,0]
	v_pk_mul_f32 v[74:75], v[74:75], v[160:161] op_sel_hi:[1,0]
	v_pk_mul_f32 v[56:57], v[56:57], v[160:161] op_sel_hi:[1,0]
	v_pk_mul_f32 v[54:55], v[54:55], v[160:161] op_sel_hi:[1,0]
	v_pk_mul_f32 v[52:53], v[52:53], v[160:161] op_sel_hi:[1,0]
	v_pk_mul_f32 v[50:51], v[50:51], v[160:161] op_sel_hi:[1,0]
	v_pk_mul_f32 v[48:49], v[48:49], v[160:161] op_sel_hi:[1,0]
	v_pk_mul_f32 v[46:47], v[46:47], v[160:161] op_sel_hi:[1,0]
	v_xor_b32_e32 v160, 0x80000000, v161
	s_branch .LBB0_566

.LBB0_569:
	v_lshl_add_u32 v180, v143, 1, v210
	v_fmamk_f32 v106, v106, 0x3e16c740, v160
	v_fmamk_f32 v107, v107, 0x3e16c740, v160
	v_fmamk_f32 v108, v108, 0x3e16c740, v160
	v_fmamk_f32 v109, v109, 0x3e16c740, v160
	v_fmamk_f32 v98, v98, 0x3e16c740, v160
	v_fmamk_f32 v99, v99, 0x3e16c740, v160
	v_fmamk_f32 v100, v100, 0x3e16c740, v160
	v_fmamk_f32 v101, v101, 0x3e16c740, v160
	v_fmamk_f32 v102, v102, 0x3e16c740, v160
	v_fmamk_f32 v103, v103, 0x3e16c740, v160
	v_fmamk_f32 v104, v104, 0x3e16c740, v160
	v_fmamk_f32 v105, v105, 0x3e16c740, v160
	v_fmamk_f32 v94, v94, 0x3e16c740, v160
	v_fmamk_f32 v95, v95, 0x3e16c740, v160
	v_fmamk_f32 v96, v96, 0x3e16c740, v160
	v_fmac_f32_e32 v160, 0x3e16c740, v97
	v_fmamk_f32 v90, v90, 0x3e16c740, v144
	v_fmamk_f32 v91, v91, 0x3e16c740, v144
	v_fmamk_f32 v92, v92, 0x3e16c740, v144
	v_fmamk_f32 v93, v93, 0x3e16c740, v144
	v_fmamk_f32 v82, v82, 0x3e16c740, v144
	v_fmamk_f32 v83, v83, 0x3e16c740, v144
	v_fmamk_f32 v84, v84, 0x3e16c740, v144
	v_fmamk_f32 v85, v85, 0x3e16c740, v144
	v_fmamk_f32 v86, v86, 0x3e16c740, v144
	v_fmamk_f32 v87, v87, 0x3e16c740, v144
	v_fmamk_f32 v88, v88, 0x3e16c740, v144
	v_fmamk_f32 v89, v89, 0x3e16c740, v144
	v_fmamk_f32 v78, v78, 0x3e16c740, v144
	v_fmamk_f32 v79, v79, 0x3e16c740, v144
	v_fmamk_f32 v80, v80, 0x3e16c740, v144
	v_fmac_f32_e32 v144, 0x3e16c740, v81
	v_add_u32_e32 v143, v133, v180
	v_exp_f32_e32 v97, v160
	v_exp_f32_e32 v81, v144
	ds_read_b64_tr_b16 v[160:161], v142 offset:64768
	ds_read_b64_tr_b16 v[158:159], v142 offset:62464
	ds_read_b64_tr_b16 v[166:167], v142 offset:64800
	ds_read_b64_tr_b16 v[164:165], v142 offset:62496
	v_add_u32_e32 v144, v134, v180
	ds_read_b64_tr_b16 v[168:169], v143
	ds_read_b64_tr_b16 v[170:171], v143 offset:2304
	ds_read_b64_tr_b16 v[172:173], v144
	ds_read_b64_tr_b16 v[174:175], v144 offset:2304
	v_exp_f32_e32 v106, v106
	v_exp_f32_e32 v107, v107
	v_exp_f32_e32 v108, v108
	v_exp_f32_e32 v109, v109
	v_exp_f32_e32 v98, v98
	v_exp_f32_e32 v99, v99
	v_exp_f32_e32 v100, v100
	v_exp_f32_e32 v101, v101
	v_exp_f32_e32 v102, v102
	v_exp_f32_e32 v103, v103
	v_exp_f32_e32 v104, v104
	v_exp_f32_e32 v105, v105
	v_exp_f32_e32 v94, v94
	v_exp_f32_e32 v95, v95
	v_exp_f32_e32 v96, v96
	v_exp_f32_e32 v90, v90
	v_exp_f32_e32 v91, v91
	v_exp_f32_e32 v92, v92
	v_exp_f32_e32 v93, v93
	v_exp_f32_e32 v82, v82
	v_exp_f32_e32 v83, v83
	v_exp_f32_e32 v84, v84
	v_exp_f32_e32 v85, v85
	v_exp_f32_e32 v86, v86
	v_exp_f32_e32 v87, v87
	v_exp_f32_e32 v88, v88
	v_exp_f32_e32 v89, v89
	v_exp_f32_e32 v78, v78
	v_exp_f32_e32 v79, v79
	v_exp_f32_e32 v80, v80
	v_cvt_pk_bf16_f32 v146, v106, v107
	v_cvt_pk_bf16_f32 v147, v108, v109
	v_cvt_pk_bf16_f32 v148, v98, v99
	v_cvt_pk_bf16_f32 v149, v100, v101
	v_cvt_pk_bf16_f32 v150, v102, v103
	v_cvt_pk_bf16_f32 v151, v104, v105
	v_cvt_pk_bf16_f32 v152, v94, v95
	v_cvt_pk_bf16_f32 v153, v96, v97
	v_cvt_pk_bf16_f32 v154, v90, v91
	v_cvt_pk_bf16_f32 v155, v92, v93
	v_cvt_pk_bf16_f32 v156, v82, v83
	v_cvt_pk_bf16_f32 v157, v84, v85
	v_cvt_pk_bf16_f32 v176, v86, v87
	v_cvt_pk_bf16_f32 v177, v88, v89
	v_cvt_pk_bf16_f32 v178, v78, v79
	v_cvt_pk_bf16_f32 v179, v80, v81
	s_setprio 1
	s_waitcnt lgkmcnt(6)
	v_mfma_f32_16x16x32_bf16 v[74:77], v[158:161], v[146:149], v[74:77]
	v_mfma_f32_16x16x32_bf16 v[58:61], v[158:161], v[154:157], v[58:61]
	s_waitcnt lgkmcnt(4)
	v_mfma_f32_16x16x32_bf16 v[54:57], v[164:167], v[146:149], v[54:57]
	v_mfma_f32_16x16x32_bf16 v[158:161], v[164:167], v[154:157], v[70:73]
	s_waitcnt lgkmcnt(2)
	v_mfma_f32_16x16x32_bf16 v[74:77], v[168:171], v[150:153], v[74:77]
	v_mfma_f32_16x16x32_bf16 v[58:61], v[168:171], v[176:179], v[58:61]
	s_waitcnt lgkmcnt(0)
	v_mfma_f32_16x16x32_bf16 v[70:73], v[172:175], v[150:153], v[54:57]
	v_mfma_f32_16x16x32_bf16 v[54:57], v[172:175], v[176:179], v[158:161]
	s_setprio 0
	v_add_u32_e32 v166, v135, v180
	v_add_u32_e32 v170, v136, v180
	ds_read_b64_tr_b16 v[160:161], v142 offset:64832
	ds_read_b64_tr_b16 v[158:159], v142 offset:62528
	ds_read_b64_tr_b16 v[144:145], v142 offset:64864
	ds_read_b64_tr_b16 v[142:143], v142 offset:62560
	ds_read_b64_tr_b16 v[164:165], v166
	ds_read_b64_tr_b16 v[166:167], v166 offset:2304
	ds_read_b64_tr_b16 v[168:169], v170
	ds_read_b64_tr_b16 v[170:171], v170 offset:2304
	s_setprio 1
	s_waitcnt lgkmcnt(6)
	v_mfma_f32_16x16x32_bf16 v[50:53], v[158:161], v[146:149], v[50:53]
	v_mfma_f32_16x16x32_bf16 v[158:161], v[158:161], v[154:157], v[66:69]
	s_waitcnt lgkmcnt(4)
	v_mfma_f32_16x16x32_bf16 v[46:49], v[142:145], v[146:149], v[46:49]
	v_mfma_f32_16x16x32_bf16 v[142:145], v[142:145], v[154:157], v[62:65]
	s_waitcnt lgkmcnt(2)
	v_mfma_f32_16x16x32_bf16 v[66:69], v[164:167], v[150:153], v[50:53]
	v_mfma_f32_16x16x32_bf16 v[50:53], v[164:167], v[176:179], v[158:161]
	s_waitcnt lgkmcnt(0)
	v_mfma_f32_16x16x32_bf16 v[62:65], v[168:171], v[150:153], v[46:49]
	v_mfma_f32_16x16x32_bf16 v[46:49], v[168:171], v[176:179], v[142:145]
	s_setprio 0
	s_andn2_b64 vcc, exec, s[2:3]
	s_cbranch_vccnz .LBB0_556
	s_xor_b32 s5, s5, 0x80
	s_cmp_eq_u32 s5, 0
	s_cbranch_scc1 .Lmla_stage_buf0
	s_waitcnt vmcnt(4)
	ds_write_b128 v224, v[10:13] offset:26624
	s_waitcnt vmcnt(3)
	ds_write_b128 v229, v[14:17] offset:53248
	s_waitcnt vmcnt(2)
	ds_write_b128 v226, v[18:21] offset:26624
	s_waitcnt vmcnt(1)
	ds_write_b128 v230, v[22:25] offset:53248
	s_waitcnt vmcnt(0)
	ds_write_b128 v228, v[34:37] offset:26752
	s_branch .LBB0_556
.Lmla_stage_buf0:
	s_waitcnt vmcnt(4)
	ds_write_b128 v224, v[10:13]
	s_waitcnt vmcnt(3)
	ds_write_b128 v225, v[14:17] offset:53248
	s_waitcnt vmcnt(2)
	ds_write_b128 v226, v[18:21]
	s_waitcnt vmcnt(1)
	ds_write_b128 v227, v[22:25] offset:53248
	s_waitcnt vmcnt(0)
	ds_write_b128 v228, v[34:37] offset:128
	s_branch .LBB0_556
